# chain step: recurrence-critical MFMAs first, output terms and next-chunk flag read in their shadow
# baseline (speedup 1.0000x reference)
; __device__ void phase_rwkv_dist(const Params& p, LAS unsigned char* lds, int wg, int nwg) {
;     ...
;         if (wave == 0) {
;             __builtin_amdgcn_s_setprio(3);
;             f32x4 Sacc[4];
; #pragma unroll
;             for (int ct = 0; ct < 4; ++ct) Sacc[ct] = zero4;
;             for (int ci = 0; ci < RC_NCHK; ++ci) {
;                 { unsigned sp = 0; while (!dead && lflag[ci % RD_NL] != (unsigned)(ci + 1)) { __builtin_amdgcn_s_sleep(1); if (++sp > RD_SPIN_MAX) { if (lane == 0) atomicAdd(ERR, 1u); dead = true; } } }
;                 asm volatile("" ::: "memory");
;                 LAS const unsigned char* sl = lds + (ci % RD_NL) * RC_SL;
;                 const bf16x8 at0 = *(LAS const bf16x8*)(sl + RC_AT + lane * 16), at1 = *(LAS const bf16x8*)(sl + RC_AT + 1024 + lane * 16);
;                 const bf16x8 rt0 = *(LAS const bf16x8*)(sl + RC_RT + lane * 16), rt1 = *(LAS const bf16x8*)(sl + RC_RT + 1024 + lane * 16);
;                 const bf16x8 mm0 = *(LAS const bf16x8*)(sl + RD_MM + lane * 32), mm1 = *(LAS const bf16x8*)(sl + RD_MM + lane * 32 + 16);
;                 const bf16x4 vt = *(LAS const bf16x4*)(sl + RC_VT + lane * 8);
;                 bf16x8 bk[4]; f32x4 gl[4];
; #pragma unroll
;                 for (int ct = 0; ct < 4; ++ct) { bk[ct] = *(LAS const bf16x8*)(sl + RD_BK + (ct * 64 + lane) * 16); gl[ct] = *(LAS const f32x4*)(sl + RC_GL + (16 * ct + 4 * q) * 4); }
;                 asm volatile("s_waitcnt lgkmcnt(0)" ::: "memory");
;                 lflag[12] = (unsigned)(ci + 1);
;                 const bf16x4 mak = __builtin_shufflevector(mm0, mm0, 0, 1, 2, 3), mrb = __builtin_shufflevector(mm0, mm0, 4, 5, 6, 7), mrk = __builtin_shufflevector(mm1, mm1, 0, 1, 2, 3), ti = __builtin_shufflevector(mm1, mm1, 4, 5, 6, 7);
;                 const bf16x8 sop0 = pk8(Sacc[0], Sacc[1]), sop1 = pk8(Sacc[2], Sacc[3]);
;                 f32x4 X = MFMA32(at0, sop0, zero4); X = MFMA32(at1, sop1, X); X = MFMA16(mak, vt, X);
;                 const f32x4 U = MFMA16(ti, pk4(X), zero4);
;                 const bf16x4 up = pk4(U);
;                 f32x4 Y = MFMA32(rt0, sop0, zero4); Y = MFMA32(rt1, sop1, Y); Y = MFMA16(mrb, up, Y); Y = MFMA16(mrk, vt, Y);
; #pragma unroll
;                 for (int ct = 0; ct < 4; ++ct) { const bf16x4 btc = __builtin_shufflevector(bk[ct], bk[ct], 0, 1, 2, 3), ktc = __builtin_shufflevector(bk[ct], bk[ct], 4, 5, 6, 7);
.LBB0_777:
	v_mov_b32_e32 v185, 0
	s_setprio 3
	s_ashr_i32 s17, s16, 31
	s_lshl_b64 s[0:1], s[16:17], 13
	s_lshl_b32 s72, s72, 5
	v_mov_b32_e32 v56, 0
	v_mov_b32_e32 v3, s1
	v_or_b32_e32 v2, s0, v148
	v_lshl_add_u64 v[68:69], v[152:153], 0, s[72:73]
	s_mov_b32 s6, 0
	s_mov_b64 s[0:1], 0
	v_mov_b32_e32 v57, v56
	v_mov_b32_e32 v58, v56
	v_mov_b32_e32 v59, v56
	v_mov_b32_e32 v64, v56
	v_mov_b32_e32 v65, v56
	v_mov_b32_e32 v66, v56
	v_mov_b32_e32 v67, v56
	v_mov_b32_e32 v60, v56
	v_mov_b32_e32 v61, v56
	v_mov_b32_e32 v62, v56
	v_mov_b32_e32 v63, v56
	s_waitcnt lgkmcnt(0)
	v_mov_b32_e32 v52, v56
	v_mov_b32_e32 v53, v56
	v_mov_b32_e32 v54, v56
	v_mov_b32_e32 v55, v56
	s_branch .LBB0_779
.LBB0_778:
	s_waitcnt lgkmcnt(0)
	s_mulk_i32 s16, 0x2b00
	s_add_i32 s2, s16, 0
	s_mul_hi_u32 s98, s7, 0xaaaaaaab
	s_lshr_b32 s98, s98, 3
	s_mul_i32 s98, s98, 12
	s_sub_i32 s98, s7, s98
	s_lshl_b32 s98, s98, 2
	s_add_i32 s98, s98, 0x27400
	v_add_u32_e32 v0, s2, v196
	v_add_u32_e32 v90, s2, v198
	v_add_u32_e32 v82, s2, v203
	v_add_u32_e32 v98, s2, v189
	ds_read_b128 v[104:107], v0
	ds_read_b128 v[108:111], v0 offset:1024
	ds_read_b128 v[112:115], v90 offset:8192
	ds_read_b64 v[102:103], v82 offset:10240
	ds_read_b128 v[120:123], v90 offset:8208
	ds_read_b128 v[116:119], v0 offset:2048
	ds_read_b128 v[128:131], v0 offset:3072
	ds_read_b128 v[132:135], v0 offset:4096
	ds_read_b128 v[136:139], v0 offset:5120
	ds_read_b128 v[140:143], v0 offset:6144
	ds_read_b128 v[144:147], v0 offset:7168
	ds_read_b128 v[124:127], v98 offset:10752
	ds_read_b128 v[160:163], v98 offset:10816
	ds_read_b128 v[168:171], v98 offset:10880
	ds_read_b128 v[176:179], v98 offset:10944
	v_cvt_pk_bf16_f32 v82, v56, v57
	v_cvt_pk_bf16_f32 v83, v58, v59
	v_cvt_pk_bf16_f32 v84, v64, v65
	v_cvt_pk_bf16_f32 v85, v66, v67
	v_cvt_pk_bf16_f32 v86, v60, v61
	v_cvt_pk_bf16_f32 v87, v62, v63
	v_cvt_pk_bf16_f32 v88, v52, v53
	v_cvt_pk_bf16_f32 v89, v54, v55
	s_lshl_b32 s72, s6, 4
	s_cmpk_eq_i32 s7, 0x200
	s_mov_b32 s6, s7
	s_waitcnt lgkmcnt(14)
	v_mfma_f32_16x16x32_bf16 v[70:73], v[104:107], v[82:85], 0
	s_waitcnt lgkmcnt(13)
	v_mfma_f32_16x16x32_bf16 v[70:73], v[108:111], v[86:89], v[70:73]
	s_waitcnt lgkmcnt(9)
	v_mfma_f32_16x16x32_bf16 v[180:183], v[116:119], v[82:85], 0
	s_waitcnt lgkmcnt(8)
	v_mfma_f32_16x16x32_bf16 v[180:183], v[128:131], v[86:89], v[180:183]
	s_nop 4
	v_mfma_f32_16x16x16_bf16 v[70:73], v[112:113], v[102:103], v[70:73]
	s_nop 7
	v_cvt_pk_bf16_f32 v70, v70, v71
	v_cvt_pk_bf16_f32 v71, v72, v73
	s_nop 1
	v_mfma_f32_16x16x16_bf16 v[70:73], v[122:123], v[70:71], 0
	s_nop 3
	v_mfma_f32_16x16x16_bf16 v[180:183], v[120:121], v[102:103], v[180:183]
	s_nop 2
	v_cvt_pk_bf16_f32 v88, v70, v71
	v_cvt_pk_bf16_f32 v89, v72, v73
	s_waitcnt lgkmcnt(4)
	s_nop 0
	v_mfma_f32_16x16x16_bf16 v[56:59], v[132:133], v[88:89], v[56:59]
	v_mfma_f32_16x16x16_bf16 v[64:67], v[136:137], v[88:89], v[64:67]
	v_mfma_f32_16x16x16_bf16 v[60:63], v[140:141], v[88:89], v[60:63]
	v_mfma_f32_16x16x16_bf16 v[52:55], v[144:145], v[88:89], v[52:55]
	v_mfma_f32_16x16x16_bf16 v[56:59], v[134:135], v[102:103], v[56:59]
	v_mfma_f32_16x16x16_bf16 v[64:67], v[138:139], v[102:103], v[64:67]
	v_mfma_f32_16x16x16_bf16 v[60:63], v[142:143], v[102:103], v[60:63]
	v_mfma_f32_16x16x16_bf16 v[52:55], v[146:147], v[102:103], v[52:55]
	v_mfma_f32_16x16x16_bf16 v[180:183], v[114:115], v[88:89], v[180:183]
	s_waitcnt lgkmcnt(0)
	v_mov_b32_e32 v0, s50
	v_mov_b32_e32 v184, s7
	ds_write_b32 v0, v184
	v_mov_b32_e32 v185, s98
	ds_read_b32 v185, v185
	v_pk_mul_f32 v[56:57], v[124:125], v[56:57]
	v_pk_mul_f32 v[58:59], v[126:127], v[58:59]
	v_pk_mul_f32 v[64:65], v[160:161], v[64:65]
	v_pk_mul_f32 v[66:67], v[162:163], v[66:67]
	v_pk_mul_f32 v[60:61], v[168:169], v[60:61]
	v_pk_mul_f32 v[62:63], v[170:171], v[62:63]
	v_pk_mul_f32 v[52:53], v[176:177], v[52:53]
	v_pk_mul_f32 v[54:55], v[178:179], v[54:55]
	v_cvt_pk_bf16_f32 v70, v180, v181
	v_cvt_pk_bf16_f32 v71, v182, v183
	v_lshl_add_u64 v[166:167], v[2:3], 0, s[72:73]
	v_lshlrev_b64 v[166:167], 7, v[166:167]
	v_mfma_f32_16x16x16_bf16 v[70:73], v[70:71], v[150:151], 0
	v_lshl_add_u64 v[166:167], v[68:69], 0, v[166:167]
	s_nop 7
	v_cvt_pk_bf16_f32 v70, v70, v71
	v_cvt_pk_bf16_f32 v71, v72, v73
	global_store_dwordx2 v[166:167], v[70:71], off
	s_cbranch_scc1 .LBB0_789
.LBB0_779:
	s_mul_hi_u32 s2, s6, 0xaaaaaaab
	s_lshr_b32 s2, s2, 3
	s_mul_i32 s2, s2, 12
	s_sub_i32 s16, s6, s2
	s_add_i32 s7, s6, 1
	s_and_b64 vcc, exec, s[0:1]
	s_mov_b64 s[0:1], -1
	s_cbranch_vccnz .LBB0_778
	s_lshl_b32 s0, s16, 2
	s_add_i32 s17, s0, 0
	s_add_i32 s17, s17, 0x27400
	s_mov_b32 s18, 0
	s_waitcnt lgkmcnt(0)
	v_cmp_eq_u32_e32 vcc, s7, v185
	s_cbranch_vccnz .LBB0_781
	s_branch .LBB0_782
